# SGU stats loads batched (16 in flight) + gelu refactor; scan DMA issued only by staging waves
# baseline (speedup 1.0000x reference)
.LBB0_118:
	s_ashr_i32 s68, s88, 5
	s_ashr_i32 s69, s68, 31
	s_and_b32 s37, s55, 0xf80
	s_lshl_b64 s[74:75], s[68:69], 12
	s_or_b32 s48, s74, s37
	s_mov_b32 s49, s75
	v_lshl_add_u64 v[4:5], s[48:49], 0, v[66:67]
	v_mad_u64_u32 v[2:3], s[48:49], v4, s86, v[68:69]
	v_mov_b32_e32 v4, 0
	s_bfe_u32 s56, s55, 0x50007
	v_mad_i32_i24 v3, v5, s86, v3
	s_mov_b64 s[48:49], 0
	v_mov_b32_e32 v5, v4
	v_add_co_u32_e32 v6, vcc, 0x9c00000, v2
	s_nop 1
	v_addc_co_u32_e32 v7, vcc, 0, v3, vcc
	global_load_dwordx4 v[34:37], v[6:7], off offset:1024
	global_load_dwordx4 v[38:41], v[6:7], off offset:1040
	global_load_dwordx4 v[42:45], v[6:7], off offset:1056
	global_load_dwordx4 v[46:49], v[6:7], off offset:1072
	global_load_dwordx4 v[50:53], v[6:7], off offset:1088
	global_load_dwordx4 v[54:57], v[6:7], off offset:1104
	global_load_dwordx4 v[58:61], v[6:7], off offset:1120
	global_load_dwordx4 v[62:65], v[6:7], off offset:1136
	global_load_dwordx4 v[178:181], v[6:7], off offset:1152
	global_load_dwordx4 v[182:185], v[6:7], off offset:1168
	global_load_dwordx4 v[186:189], v[6:7], off offset:1184
	global_load_dwordx4 v[190:193], v[6:7], off offset:1200
	global_load_dwordx4 v[194:197], v[6:7], off offset:1216
	global_load_dwordx4 v[198:201], v[6:7], off offset:1232
	global_load_dwordx4 v[202:205], v[6:7], off offset:1248
	global_load_dwordx4 v[206:209], v[6:7], off offset:1264
	v_mov_b32_e32 v21, 0
	v_mov_b32_e32 v20, 0
	v_mov_b32_e32 v23, 0
	v_mov_b32_e32 v22, 0
	v_mov_b32_e32 v25, 0
	v_mov_b32_e32 v24, 0
	s_waitcnt vmcnt(15)
	v_lshlrev_b32_e32 v8, 16, v34
	v_and_b32_e32 v9, 0xffff0000, v34
	v_lshlrev_b32_e32 v10, 16, v35
	v_and_b32_e32 v11, 0xffff0000, v35
	v_mul_f32_e32 v12, 0xbdd2d3e7, v8
	v_mul_f32_e32 v13, 0xbdd2d3e7, v9
	v_mul_f32_e32 v14, 0xbdd2d3e7, v10
	v_mul_f32_e32 v15, 0xbdd2d3e7, v11
	v_fmaak_f32 v12, v12, v8, 0xc0135761
	v_fmaak_f32 v13, v13, v9, 0xc0135761
	v_fmaak_f32 v14, v14, v10, 0xc0135761
	v_fmaak_f32 v15, v15, v11, 0xc0135761
	v_mul_f32_e32 v12, v12, v8
	v_mul_f32_e32 v13, v13, v9
	v_mul_f32_e32 v14, v14, v10
	v_mul_f32_e32 v15, v15, v11
	v_exp_f32_e32 v12, v12
	v_exp_f32_e32 v13, v13
	v_exp_f32_e32 v14, v14
	v_exp_f32_e32 v15, v15
	v_add_f32_e32 v12, 1.0, v12
	v_add_f32_e32 v13, 1.0, v13
	v_add_f32_e32 v14, 1.0, v14
	v_add_f32_e32 v15, 1.0, v15
	v_rcp_f32_e32 v12, v12
	v_rcp_f32_e32 v13, v13
	v_rcp_f32_e32 v14, v14
	v_rcp_f32_e32 v15, v15
	v_mul_f32_e32 v12, v12, v8
	v_mul_f32_e32 v13, v13, v9
	v_mul_f32_e32 v14, v14, v10
	v_mul_f32_e32 v15, v15, v11
	v_add_f32_e32 v5, v5, v12
	v_add_f32_e32 v21, v21, v13
	v_add_f32_e32 v23, v23, v14
	v_add_f32_e32 v25, v25, v15
	v_fmac_f32_e32 v4, v12, v12
	v_fmac_f32_e32 v20, v13, v13
	v_fmac_f32_e32 v22, v14, v14
	v_fmac_f32_e32 v24, v15, v15
	v_lshlrev_b32_e32 v8, 16, v36
	v_and_b32_e32 v9, 0xffff0000, v36
	v_lshlrev_b32_e32 v10, 16, v37
	v_and_b32_e32 v11, 0xffff0000, v37
	v_mul_f32_e32 v12, 0xbdd2d3e7, v8
	v_mul_f32_e32 v13, 0xbdd2d3e7, v9
	v_mul_f32_e32 v14, 0xbdd2d3e7, v10
	v_mul_f32_e32 v15, 0xbdd2d3e7, v11
	v_fmaak_f32 v12, v12, v8, 0xc0135761
	v_fmaak_f32 v13, v13, v9, 0xc0135761
	v_fmaak_f32 v14, v14, v10, 0xc0135761
	v_fmaak_f32 v15, v15, v11, 0xc0135761
	v_mul_f32_e32 v12, v12, v8
	v_mul_f32_e32 v13, v13, v9
	v_mul_f32_e32 v14, v14, v10
	v_mul_f32_e32 v15, v15, v11
	v_exp_f32_e32 v12, v12
	v_exp_f32_e32 v13, v13
	v_exp_f32_e32 v14, v14
	v_exp_f32_e32 v15, v15
	v_add_f32_e32 v12, 1.0, v12
	v_add_f32_e32 v13, 1.0, v13
	v_add_f32_e32 v14, 1.0, v14
	v_add_f32_e32 v15, 1.0, v15
	v_rcp_f32_e32 v12, v12
	v_rcp_f32_e32 v13, v13
	v_rcp_f32_e32 v14, v14
	v_rcp_f32_e32 v15, v15
	v_mul_f32_e32 v12, v12, v8
	v_mul_f32_e32 v13, v13, v9
	v_mul_f32_e32 v14, v14, v10
	v_mul_f32_e32 v15, v15, v11
	v_add_f32_e32 v5, v5, v12
	v_add_f32_e32 v21, v21, v13
	v_add_f32_e32 v23, v23, v14
	v_add_f32_e32 v25, v25, v15
	v_fmac_f32_e32 v4, v12, v12
	v_fmac_f32_e32 v20, v13, v13
	v_fmac_f32_e32 v22, v14, v14
	v_fmac_f32_e32 v24, v15, v15
	s_waitcnt vmcnt(14)
	v_lshlrev_b32_e32 v8, 16, v38
	v_and_b32_e32 v9, 0xffff0000, v38
	v_lshlrev_b32_e32 v10, 16, v39
	v_and_b32_e32 v11, 0xffff0000, v39
	v_mul_f32_e32 v12, 0xbdd2d3e7, v8
	v_mul_f32_e32 v13, 0xbdd2d3e7, v9
	v_mul_f32_e32 v14, 0xbdd2d3e7, v10
	v_mul_f32_e32 v15, 0xbdd2d3e7, v11
	v_fmaak_f32 v12, v12, v8, 0xc0135761
	v_fmaak_f32 v13, v13, v9, 0xc0135761
	v_fmaak_f32 v14, v14, v10, 0xc0135761
	v_fmaak_f32 v15, v15, v11, 0xc0135761
	v_mul_f32_e32 v12, v12, v8
	v_mul_f32_e32 v13, v13, v9
	v_mul_f32_e32 v14, v14, v10
	v_mul_f32_e32 v15, v15, v11
	v_exp_f32_e32 v12, v12
	v_exp_f32_e32 v13, v13
	v_exp_f32_e32 v14, v14
	v_exp_f32_e32 v15, v15
	v_add_f32_e32 v12, 1.0, v12
	v_add_f32_e32 v13, 1.0, v13
	v_add_f32_e32 v14, 1.0, v14
	v_add_f32_e32 v15, 1.0, v15
	v_rcp_f32_e32 v12, v12
	v_rcp_f32_e32 v13, v13
	v_rcp_f32_e32 v14, v14
	v_rcp_f32_e32 v15, v15
	v_mul_f32_e32 v12, v12, v8
	v_mul_f32_e32 v13, v13, v9
	v_mul_f32_e32 v14, v14, v10
	v_mul_f32_e32 v15, v15, v11
	v_add_f32_e32 v5, v5, v12
	v_add_f32_e32 v21, v21, v13
	v_add_f32_e32 v23, v23, v14
	v_add_f32_e32 v25, v25, v15
	v_fmac_f32_e32 v4, v12, v12
	v_fmac_f32_e32 v20, v13, v13
	v_fmac_f32_e32 v22, v14, v14
	v_fmac_f32_e32 v24, v15, v15
	v_lshlrev_b32_e32 v8, 16, v40
	v_and_b32_e32 v9, 0xffff0000, v40
	v_lshlrev_b32_e32 v10, 16, v41
	v_and_b32_e32 v11, 0xffff0000, v41
	v_mul_f32_e32 v12, 0xbdd2d3e7, v8
	v_mul_f32_e32 v13, 0xbdd2d3e7, v9
	v_mul_f32_e32 v14, 0xbdd2d3e7, v10
	v_mul_f32_e32 v15, 0xbdd2d3e7, v11
	v_fmaak_f32 v12, v12, v8, 0xc0135761
	v_fmaak_f32 v13, v13, v9, 0xc0135761
	v_fmaak_f32 v14, v14, v10, 0xc0135761
	v_fmaak_f32 v15, v15, v11, 0xc0135761
	v_mul_f32_e32 v12, v12, v8
	v_mul_f32_e32 v13, v13, v9
	v_mul_f32_e32 v14, v14, v10
	v_mul_f32_e32 v15, v15, v11
	v_exp_f32_e32 v12, v12
	v_exp_f32_e32 v13, v13
	v_exp_f32_e32 v14, v14
	v_exp_f32_e32 v15, v15
	v_add_f32_e32 v12, 1.0, v12
	v_add_f32_e32 v13, 1.0, v13
	v_add_f32_e32 v14, 1.0, v14
	v_add_f32_e32 v15, 1.0, v15
	v_rcp_f32_e32 v12, v12
	v_rcp_f32_e32 v13, v13
	v_rcp_f32_e32 v14, v14
	v_rcp_f32_e32 v15, v15
	v_mul_f32_e32 v12, v12, v8
	v_mul_f32_e32 v13, v13, v9
	v_mul_f32_e32 v14, v14, v10
	v_mul_f32_e32 v15, v15, v11
	v_add_f32_e32 v5, v5, v12
	v_add_f32_e32 v21, v21, v13
	v_add_f32_e32 v23, v23, v14
	v_add_f32_e32 v25, v25, v15
	v_fmac_f32_e32 v4, v12, v12
	v_fmac_f32_e32 v20, v13, v13
	v_fmac_f32_e32 v22, v14, v14
	v_fmac_f32_e32 v24, v15, v15
	s_waitcnt vmcnt(13)
	v_lshlrev_b32_e32 v8, 16, v42
	v_and_b32_e32 v9, 0xffff0000, v42
	v_lshlrev_b32_e32 v10, 16, v43
	v_and_b32_e32 v11, 0xffff0000, v43
	v_mul_f32_e32 v12, 0xbdd2d3e7, v8
	v_mul_f32_e32 v13, 0xbdd2d3e7, v9
	v_mul_f32_e32 v14, 0xbdd2d3e7, v10
	v_mul_f32_e32 v15, 0xbdd2d3e7, v11
	v_fmaak_f32 v12, v12, v8, 0xc0135761
	v_fmaak_f32 v13, v13, v9, 0xc0135761
	v_fmaak_f32 v14, v14, v10, 0xc0135761
	v_fmaak_f32 v15, v15, v11, 0xc0135761
	v_mul_f32_e32 v12, v12, v8
	v_mul_f32_e32 v13, v13, v9
	v_mul_f32_e32 v14, v14, v10
	v_mul_f32_e32 v15, v15, v11
	v_exp_f32_e32 v12, v12
	v_exp_f32_e32 v13, v13
	v_exp_f32_e32 v14, v14
	v_exp_f32_e32 v15, v15
	v_add_f32_e32 v12, 1.0, v12
	v_add_f32_e32 v13, 1.0, v13
	v_add_f32_e32 v14, 1.0, v14
	v_add_f32_e32 v15, 1.0, v15
	v_rcp_f32_e32 v12, v12
	v_rcp_f32_e32 v13, v13
	v_rcp_f32_e32 v14, v14
	v_rcp_f32_e32 v15, v15
	v_mul_f32_e32 v12, v12, v8
	v_mul_f32_e32 v13, v13, v9
	v_mul_f32_e32 v14, v14, v10
	v_mul_f32_e32 v15, v15, v11
	v_add_f32_e32 v5, v5, v12
	v_add_f32_e32 v21, v21, v13
	v_add_f32_e32 v23, v23, v14
	v_add_f32_e32 v25, v25, v15
	v_fmac_f32_e32 v4, v12, v12
	v_fmac_f32_e32 v20, v13, v13
	v_fmac_f32_e32 v22, v14, v14
	v_fmac_f32_e32 v24, v15, v15
	v_lshlrev_b32_e32 v8, 16, v44
	v_and_b32_e32 v9, 0xffff0000, v44
	v_lshlrev_b32_e32 v10, 16, v45
	v_and_b32_e32 v11, 0xffff0000, v45
	v_mul_f32_e32 v12, 0xbdd2d3e7, v8
	v_mul_f32_e32 v13, 0xbdd2d3e7, v9
	v_mul_f32_e32 v14, 0xbdd2d3e7, v10
	v_mul_f32_e32 v15, 0xbdd2d3e7, v11
	v_fmaak_f32 v12, v12, v8, 0xc0135761
	v_fmaak_f32 v13, v13, v9, 0xc0135761
	v_fmaak_f32 v14, v14, v10, 0xc0135761
	v_fmaak_f32 v15, v15, v11, 0xc0135761
	v_mul_f32_e32 v12, v12, v8
	v_mul_f32_e32 v13, v13, v9
	v_mul_f32_e32 v14, v14, v10
	v_mul_f32_e32 v15, v15, v11
	v_exp_f32_e32 v12, v12
	v_exp_f32_e32 v13, v13
	v_exp_f32_e32 v14, v14
	v_exp_f32_e32 v15, v15
	v_add_f32_e32 v12, 1.0, v12
	v_add_f32_e32 v13, 1.0, v13
	v_add_f32_e32 v14, 1.0, v14
	v_add_f32_e32 v15, 1.0, v15
	v_rcp_f32_e32 v12, v12
	v_rcp_f32_e32 v13, v13
	v_rcp_f32_e32 v14, v14
	v_rcp_f32_e32 v15, v15
	v_mul_f32_e32 v12, v12, v8
	v_mul_f32_e32 v13, v13, v9
	v_mul_f32_e32 v14, v14, v10
	v_mul_f32_e32 v15, v15, v11
	v_add_f32_e32 v5, v5, v12
	v_add_f32_e32 v21, v21, v13
	v_add_f32_e32 v23, v23, v14
	v_add_f32_e32 v25, v25, v15
	v_fmac_f32_e32 v4, v12, v12
	v_fmac_f32_e32 v20, v13, v13
	v_fmac_f32_e32 v22, v14, v14
	v_fmac_f32_e32 v24, v15, v15
	s_waitcnt vmcnt(12)
	v_lshlrev_b32_e32 v8, 16, v46
	v_and_b32_e32 v9, 0xffff0000, v46
	v_lshlrev_b32_e32 v10, 16, v47
	v_and_b32_e32 v11, 0xffff0000, v47
	v_mul_f32_e32 v12, 0xbdd2d3e7, v8
	v_mul_f32_e32 v13, 0xbdd2d3e7, v9
	v_mul_f32_e32 v14, 0xbdd2d3e7, v10
	v_mul_f32_e32 v15, 0xbdd2d3e7, v11
	v_fmaak_f32 v12, v12, v8, 0xc0135761
	v_fmaak_f32 v13, v13, v9, 0xc0135761
	v_fmaak_f32 v14, v14, v10, 0xc0135761
	v_fmaak_f32 v15, v15, v11, 0xc0135761
	v_mul_f32_e32 v12, v12, v8
	v_mul_f32_e32 v13, v13, v9
	v_mul_f32_e32 v14, v14, v10
	v_mul_f32_e32 v15, v15, v11
	v_exp_f32_e32 v12, v12
	v_exp_f32_e32 v13, v13
	v_exp_f32_e32 v14, v14
	v_exp_f32_e32 v15, v15
	v_add_f32_e32 v12, 1.0, v12
	v_add_f32_e32 v13, 1.0, v13
	v_add_f32_e32 v14, 1.0, v14
	v_add_f32_e32 v15, 1.0, v15
	v_rcp_f32_e32 v12, v12
	v_rcp_f32_e32 v13, v13
	v_rcp_f32_e32 v14, v14
	v_rcp_f32_e32 v15, v15
	v_mul_f32_e32 v12, v12, v8
	v_mul_f32_e32 v13, v13, v9
	v_mul_f32_e32 v14, v14, v10
	v_mul_f32_e32 v15, v15, v11
	v_add_f32_e32 v5, v5, v12
	v_add_f32_e32 v21, v21, v13
	v_add_f32_e32 v23, v23, v14
	v_add_f32_e32 v25, v25, v15
	v_fmac_f32_e32 v4, v12, v12
	v_fmac_f32_e32 v20, v13, v13
	v_fmac_f32_e32 v22, v14, v14
	v_fmac_f32_e32 v24, v15, v15
	v_lshlrev_b32_e32 v8, 16, v48
	v_and_b32_e32 v9, 0xffff0000, v48
	v_lshlrev_b32_e32 v10, 16, v49
	v_and_b32_e32 v11, 0xffff0000, v49
	v_mul_f32_e32 v12, 0xbdd2d3e7, v8
	v_mul_f32_e32 v13, 0xbdd2d3e7, v9
	v_mul_f32_e32 v14, 0xbdd2d3e7, v10
	v_mul_f32_e32 v15, 0xbdd2d3e7, v11
	v_fmaak_f32 v12, v12, v8, 0xc0135761
	v_fmaak_f32 v13, v13, v9, 0xc0135761
	v_fmaak_f32 v14, v14, v10, 0xc0135761
	v_fmaak_f32 v15, v15, v11, 0xc0135761
	v_mul_f32_e32 v12, v12, v8
	v_mul_f32_e32 v13, v13, v9
	v_mul_f32_e32 v14, v14, v10
	v_mul_f32_e32 v15, v15, v11
	v_exp_f32_e32 v12, v12
	v_exp_f32_e32 v13, v13
	v_exp_f32_e32 v14, v14
	v_exp_f32_e32 v15, v15
	v_add_f32_e32 v12, 1.0, v12
	v_add_f32_e32 v13, 1.0, v13
	v_add_f32_e32 v14, 1.0, v14
	v_add_f32_e32 v15, 1.0, v15
	v_rcp_f32_e32 v12, v12
	v_rcp_f32_e32 v13, v13
	v_rcp_f32_e32 v14, v14
	v_rcp_f32_e32 v15, v15
	v_mul_f32_e32 v12, v12, v8
	v_mul_f32_e32 v13, v13, v9
	v_mul_f32_e32 v14, v14, v10
	v_mul_f32_e32 v15, v15, v11
	v_add_f32_e32 v5, v5, v12
	v_add_f32_e32 v21, v21, v13
	v_add_f32_e32 v23, v23, v14
	v_add_f32_e32 v25, v25, v15
	v_fmac_f32_e32 v4, v12, v12
	v_fmac_f32_e32 v20, v13, v13
	v_fmac_f32_e32 v22, v14, v14
	v_fmac_f32_e32 v24, v15, v15
	s_waitcnt vmcnt(11)
	v_lshlrev_b32_e32 v8, 16, v50
	v_and_b32_e32 v9, 0xffff0000, v50
	v_lshlrev_b32_e32 v10, 16, v51
	v_and_b32_e32 v11, 0xffff0000, v51
	v_mul_f32_e32 v12, 0xbdd2d3e7, v8
	v_mul_f32_e32 v13, 0xbdd2d3e7, v9
	v_mul_f32_e32 v14, 0xbdd2d3e7, v10
	v_mul_f32_e32 v15, 0xbdd2d3e7, v11
	v_fmaak_f32 v12, v12, v8, 0xc0135761
	v_fmaak_f32 v13, v13, v9, 0xc0135761
	v_fmaak_f32 v14, v14, v10, 0xc0135761
	v_fmaak_f32 v15, v15, v11, 0xc0135761
	v_mul_f32_e32 v12, v12, v8
	v_mul_f32_e32 v13, v13, v9
	v_mul_f32_e32 v14, v14, v10
	v_mul_f32_e32 v15, v15, v11
	v_exp_f32_e32 v12, v12
	v_exp_f32_e32 v13, v13
	v_exp_f32_e32 v14, v14
	v_exp_f32_e32 v15, v15
	v_add_f32_e32 v12, 1.0, v12
	v_add_f32_e32 v13, 1.0, v13
	v_add_f32_e32 v14, 1.0, v14
	v_add_f32_e32 v15, 1.0, v15
	v_rcp_f32_e32 v12, v12
	v_rcp_f32_e32 v13, v13
	v_rcp_f32_e32 v14, v14
	v_rcp_f32_e32 v15, v15
	v_mul_f32_e32 v12, v12, v8
	v_mul_f32_e32 v13, v13, v9
	v_mul_f32_e32 v14, v14, v10
	v_mul_f32_e32 v15, v15, v11
	v_add_f32_e32 v5, v5, v12
	v_add_f32_e32 v21, v21, v13
	v_add_f32_e32 v23, v23, v14
	v_add_f32_e32 v25, v25, v15
	v_fmac_f32_e32 v4, v12, v12
	v_fmac_f32_e32 v20, v13, v13
	v_fmac_f32_e32 v22, v14, v14
	v_fmac_f32_e32 v24, v15, v15
	v_lshlrev_b32_e32 v8, 16, v52
	v_and_b32_e32 v9, 0xffff0000, v52
	v_lshlrev_b32_e32 v10, 16, v53
	v_and_b32_e32 v11, 0xffff0000, v53
	v_mul_f32_e32 v12, 0xbdd2d3e7, v8
	v_mul_f32_e32 v13, 0xbdd2d3e7, v9
	v_mul_f32_e32 v14, 0xbdd2d3e7, v10
	v_mul_f32_e32 v15, 0xbdd2d3e7, v11
	v_fmaak_f32 v12, v12, v8, 0xc0135761
	v_fmaak_f32 v13, v13, v9, 0xc0135761
	v_fmaak_f32 v14, v14, v10, 0xc0135761
	v_fmaak_f32 v15, v15, v11, 0xc0135761
	v_mul_f32_e32 v12, v12, v8
	v_mul_f32_e32 v13, v13, v9
	v_mul_f32_e32 v14, v14, v10
	v_mul_f32_e32 v15, v15, v11
	v_exp_f32_e32 v12, v12
	v_exp_f32_e32 v13, v13
	v_exp_f32_e32 v14, v14
	v_exp_f32_e32 v15, v15
	v_add_f32_e32 v12, 1.0, v12
	v_add_f32_e32 v13, 1.0, v13
	v_add_f32_e32 v14, 1.0, v14
	v_add_f32_e32 v15, 1.0, v15
	v_rcp_f32_e32 v12, v12
	v_rcp_f32_e32 v13, v13
	v_rcp_f32_e32 v14, v14
	v_rcp_f32_e32 v15, v15
	v_mul_f32_e32 v12, v12, v8
	v_mul_f32_e32 v13, v13, v9
	v_mul_f32_e32 v14, v14, v10
	v_mul_f32_e32 v15, v15, v11
	v_add_f32_e32 v5, v5, v12
	v_add_f32_e32 v21, v21, v13
	v_add_f32_e32 v23, v23, v14
	v_add_f32_e32 v25, v25, v15
	v_fmac_f32_e32 v4, v12, v12
	v_fmac_f32_e32 v20, v13, v13
	v_fmac_f32_e32 v22, v14, v14
	v_fmac_f32_e32 v24, v15, v15
	s_waitcnt vmcnt(10)
	v_lshlrev_b32_e32 v8, 16, v54
	v_and_b32_e32 v9, 0xffff0000, v54
	v_lshlrev_b32_e32 v10, 16, v55
	v_and_b32_e32 v11, 0xffff0000, v55
	v_mul_f32_e32 v12, 0xbdd2d3e7, v8
	v_mul_f32_e32 v13, 0xbdd2d3e7, v9
	v_mul_f32_e32 v14, 0xbdd2d3e7, v10
	v_mul_f32_e32 v15, 0xbdd2d3e7, v11
	v_fmaak_f32 v12, v12, v8, 0xc0135761
	v_fmaak_f32 v13, v13, v9, 0xc0135761
	v_fmaak_f32 v14, v14, v10, 0xc0135761
	v_fmaak_f32 v15, v15, v11, 0xc0135761
	v_mul_f32_e32 v12, v12, v8
	v_mul_f32_e32 v13, v13, v9
	v_mul_f32_e32 v14, v14, v10
	v_mul_f32_e32 v15, v15, v11
	v_exp_f32_e32 v12, v12
	v_exp_f32_e32 v13, v13
	v_exp_f32_e32 v14, v14
	v_exp_f32_e32 v15, v15
	v_add_f32_e32 v12, 1.0, v12
	v_add_f32_e32 v13, 1.0, v13
	v_add_f32_e32 v14, 1.0, v14
	v_add_f32_e32 v15, 1.0, v15
	v_rcp_f32_e32 v12, v12
	v_rcp_f32_e32 v13, v13
	v_rcp_f32_e32 v14, v14
	v_rcp_f32_e32 v15, v15
	v_mul_f32_e32 v12, v12, v8
	v_mul_f32_e32 v13, v13, v9
	v_mul_f32_e32 v14, v14, v10
	v_mul_f32_e32 v15, v15, v11
	v_add_f32_e32 v5, v5, v12
	v_add_f32_e32 v21, v21, v13
	v_add_f32_e32 v23, v23, v14
	v_add_f32_e32 v25, v25, v15
	v_fmac_f32_e32 v4, v12, v12
	v_fmac_f32_e32 v20, v13, v13
	v_fmac_f32_e32 v22, v14, v14
	v_fmac_f32_e32 v24, v15, v15
	v_lshlrev_b32_e32 v8, 16, v56
	v_and_b32_e32 v9, 0xffff0000, v56
	v_lshlrev_b32_e32 v10, 16, v57
	v_and_b32_e32 v11, 0xffff0000, v57
	v_mul_f32_e32 v12, 0xbdd2d3e7, v8
	v_mul_f32_e32 v13, 0xbdd2d3e7, v9
	v_mul_f32_e32 v14, 0xbdd2d3e7, v10
	v_mul_f32_e32 v15, 0xbdd2d3e7, v11
	v_fmaak_f32 v12, v12, v8, 0xc0135761
	v_fmaak_f32 v13, v13, v9, 0xc0135761
	v_fmaak_f32 v14, v14, v10, 0xc0135761
	v_fmaak_f32 v15, v15, v11, 0xc0135761
	v_mul_f32_e32 v12, v12, v8
	v_mul_f32_e32 v13, v13, v9
	v_mul_f32_e32 v14, v14, v10
	v_mul_f32_e32 v15, v15, v11
	v_exp_f32_e32 v12, v12
	v_exp_f32_e32 v13, v13
	v_exp_f32_e32 v14, v14
	v_exp_f32_e32 v15, v15
	v_add_f32_e32 v12, 1.0, v12
	v_add_f32_e32 v13, 1.0, v13
	v_add_f32_e32 v14, 1.0, v14
	v_add_f32_e32 v15, 1.0, v15
	v_rcp_f32_e32 v12, v12
	v_rcp_f32_e32 v13, v13
	v_rcp_f32_e32 v14, v14
	v_rcp_f32_e32 v15, v15
	v_mul_f32_e32 v12, v12, v8
	v_mul_f32_e32 v13, v13, v9
	v_mul_f32_e32 v14, v14, v10
	v_mul_f32_e32 v15, v15, v11
	v_add_f32_e32 v5, v5, v12
	v_add_f32_e32 v21, v21, v13
	v_add_f32_e32 v23, v23, v14
	v_add_f32_e32 v25, v25, v15
	v_fmac_f32_e32 v4, v12, v12
	v_fmac_f32_e32 v20, v13, v13
	v_fmac_f32_e32 v22, v14, v14
	v_fmac_f32_e32 v24, v15, v15
	s_waitcnt vmcnt(9)
	v_lshlrev_b32_e32 v8, 16, v58
	v_and_b32_e32 v9, 0xffff0000, v58
	v_lshlrev_b32_e32 v10, 16, v59
	v_and_b32_e32 v11, 0xffff0000, v59
	v_mul_f32_e32 v12, 0xbdd2d3e7, v8
	v_mul_f32_e32 v13, 0xbdd2d3e7, v9
	v_mul_f32_e32 v14, 0xbdd2d3e7, v10
	v_mul_f32_e32 v15, 0xbdd2d3e7, v11
	v_fmaak_f32 v12, v12, v8, 0xc0135761
	v_fmaak_f32 v13, v13, v9, 0xc0135761
	v_fmaak_f32 v14, v14, v10, 0xc0135761
	v_fmaak_f32 v15, v15, v11, 0xc0135761
	v_mul_f32_e32 v12, v12, v8
	v_mul_f32_e32 v13, v13, v9
	v_mul_f32_e32 v14, v14, v10
	v_mul_f32_e32 v15, v15, v11
	v_exp_f32_e32 v12, v12
	v_exp_f32_e32 v13, v13
	v_exp_f32_e32 v14, v14
	v_exp_f32_e32 v15, v15
	v_add_f32_e32 v12, 1.0, v12
	v_add_f32_e32 v13, 1.0, v13
	v_add_f32_e32 v14, 1.0, v14
	v_add_f32_e32 v15, 1.0, v15
	v_rcp_f32_e32 v12, v12
	v_rcp_f32_e32 v13, v13
	v_rcp_f32_e32 v14, v14
	v_rcp_f32_e32 v15, v15
	v_mul_f32_e32 v12, v12, v8
	v_mul_f32_e32 v13, v13, v9
	v_mul_f32_e32 v14, v14, v10
	v_mul_f32_e32 v15, v15, v11
	v_add_f32_e32 v5, v5, v12
	v_add_f32_e32 v21, v21, v13
	v_add_f32_e32 v23, v23, v14
	v_add_f32_e32 v25, v25, v15
	v_fmac_f32_e32 v4, v12, v12
	v_fmac_f32_e32 v20, v13, v13
	v_fmac_f32_e32 v22, v14, v14
	v_fmac_f32_e32 v24, v15, v15
	v_lshlrev_b32_e32 v8, 16, v60
	v_and_b32_e32 v9, 0xffff0000, v60
	v_lshlrev_b32_e32 v10, 16, v61
	v_and_b32_e32 v11, 0xffff0000, v61
	v_mul_f32_e32 v12, 0xbdd2d3e7, v8
	v_mul_f32_e32 v13, 0xbdd2d3e7, v9
	v_mul_f32_e32 v14, 0xbdd2d3e7, v10
	v_mul_f32_e32 v15, 0xbdd2d3e7, v11
	v_fmaak_f32 v12, v12, v8, 0xc0135761
	v_fmaak_f32 v13, v13, v9, 0xc0135761
	v_fmaak_f32 v14, v14, v10, 0xc0135761
	v_fmaak_f32 v15, v15, v11, 0xc0135761
	v_mul_f32_e32 v12, v12, v8
	v_mul_f32_e32 v13, v13, v9
	v_mul_f32_e32 v14, v14, v10
	v_mul_f32_e32 v15, v15, v11
	v_exp_f32_e32 v12, v12
	v_exp_f32_e32 v13, v13
	v_exp_f32_e32 v14, v14
	v_exp_f32_e32 v15, v15
	v_add_f32_e32 v12, 1.0, v12
	v_add_f32_e32 v13, 1.0, v13
	v_add_f32_e32 v14, 1.0, v14
	v_add_f32_e32 v15, 1.0, v15
	v_rcp_f32_e32 v12, v12
	v_rcp_f32_e32 v13, v13
	v_rcp_f32_e32 v14, v14
	v_rcp_f32_e32 v15, v15
	v_mul_f32_e32 v12, v12, v8
	v_mul_f32_e32 v13, v13, v9
	v_mul_f32_e32 v14, v14, v10
	v_mul_f32_e32 v15, v15, v11
	v_add_f32_e32 v5, v5, v12
	v_add_f32_e32 v21, v21, v13
	v_add_f32_e32 v23, v23, v14
	v_add_f32_e32 v25, v25, v15
	v_fmac_f32_e32 v4, v12, v12
	v_fmac_f32_e32 v20, v13, v13
	v_fmac_f32_e32 v22, v14, v14
	v_fmac_f32_e32 v24, v15, v15
	s_waitcnt vmcnt(8)
	v_lshlrev_b32_e32 v8, 16, v62
	v_and_b32_e32 v9, 0xffff0000, v62
	v_lshlrev_b32_e32 v10, 16, v63
	v_and_b32_e32 v11, 0xffff0000, v63
	v_mul_f32_e32 v12, 0xbdd2d3e7, v8
	v_mul_f32_e32 v13, 0xbdd2d3e7, v9
	v_mul_f32_e32 v14, 0xbdd2d3e7, v10
	v_mul_f32_e32 v15, 0xbdd2d3e7, v11
	v_fmaak_f32 v12, v12, v8, 0xc0135761
	v_fmaak_f32 v13, v13, v9, 0xc0135761
	v_fmaak_f32 v14, v14, v10, 0xc0135761
	v_fmaak_f32 v15, v15, v11, 0xc0135761
	v_mul_f32_e32 v12, v12, v8
	v_mul_f32_e32 v13, v13, v9
	v_mul_f32_e32 v14, v14, v10
	v_mul_f32_e32 v15, v15, v11
	v_exp_f32_e32 v12, v12
	v_exp_f32_e32 v13, v13
	v_exp_f32_e32 v14, v14
	v_exp_f32_e32 v15, v15
	v_add_f32_e32 v12, 1.0, v12
	v_add_f32_e32 v13, 1.0, v13
	v_add_f32_e32 v14, 1.0, v14
	v_add_f32_e32 v15, 1.0, v15
	v_rcp_f32_e32 v12, v12
	v_rcp_f32_e32 v13, v13
	v_rcp_f32_e32 v14, v14
	v_rcp_f32_e32 v15, v15
	v_mul_f32_e32 v12, v12, v8
	v_mul_f32_e32 v13, v13, v9
	v_mul_f32_e32 v14, v14, v10
	v_mul_f32_e32 v15, v15, v11
	v_add_f32_e32 v5, v5, v12
	v_add_f32_e32 v21, v21, v13
	v_add_f32_e32 v23, v23, v14
	v_add_f32_e32 v25, v25, v15
	v_fmac_f32_e32 v4, v12, v12
	v_fmac_f32_e32 v20, v13, v13
	v_fmac_f32_e32 v22, v14, v14
	v_fmac_f32_e32 v24, v15, v15
	v_lshlrev_b32_e32 v8, 16, v64
	v_and_b32_e32 v9, 0xffff0000, v64
	v_lshlrev_b32_e32 v10, 16, v65
	v_and_b32_e32 v11, 0xffff0000, v65
	v_mul_f32_e32 v12, 0xbdd2d3e7, v8
	v_mul_f32_e32 v13, 0xbdd2d3e7, v9
	v_mul_f32_e32 v14, 0xbdd2d3e7, v10
	v_mul_f32_e32 v15, 0xbdd2d3e7, v11
	v_fmaak_f32 v12, v12, v8, 0xc0135761
	v_fmaak_f32 v13, v13, v9, 0xc0135761
	v_fmaak_f32 v14, v14, v10, 0xc0135761
	v_fmaak_f32 v15, v15, v11, 0xc0135761
	v_mul_f32_e32 v12, v12, v8
	v_mul_f32_e32 v13, v13, v9
	v_mul_f32_e32 v14, v14, v10
	v_mul_f32_e32 v15, v15, v11
	v_exp_f32_e32 v12, v12
	v_exp_f32_e32 v13, v13
	v_exp_f32_e32 v14, v14
	v_exp_f32_e32 v15, v15
	v_add_f32_e32 v12, 1.0, v12
	v_add_f32_e32 v13, 1.0, v13
	v_add_f32_e32 v14, 1.0, v14
	v_add_f32_e32 v15, 1.0, v15
	v_rcp_f32_e32 v12, v12
	v_rcp_f32_e32 v13, v13
	v_rcp_f32_e32 v14, v14
	v_rcp_f32_e32 v15, v15
	v_mul_f32_e32 v12, v12, v8
	v_mul_f32_e32 v13, v13, v9
	v_mul_f32_e32 v14, v14, v10
	v_mul_f32_e32 v15, v15, v11
	v_add_f32_e32 v5, v5, v12
	v_add_f32_e32 v21, v21, v13
	v_add_f32_e32 v23, v23, v14
	v_add_f32_e32 v25, v25, v15
	v_fmac_f32_e32 v4, v12, v12
	v_fmac_f32_e32 v20, v13, v13
	v_fmac_f32_e32 v22, v14, v14
	v_fmac_f32_e32 v24, v15, v15
	s_waitcnt vmcnt(7)
	v_lshlrev_b32_e32 v8, 16, v178
	v_and_b32_e32 v9, 0xffff0000, v178
	v_lshlrev_b32_e32 v10, 16, v179
	v_and_b32_e32 v11, 0xffff0000, v179
	v_mul_f32_e32 v12, 0xbdd2d3e7, v8
	v_mul_f32_e32 v13, 0xbdd2d3e7, v9
	v_mul_f32_e32 v14, 0xbdd2d3e7, v10
	v_mul_f32_e32 v15, 0xbdd2d3e7, v11
	v_fmaak_f32 v12, v12, v8, 0xc0135761
	v_fmaak_f32 v13, v13, v9, 0xc0135761
	v_fmaak_f32 v14, v14, v10, 0xc0135761
	v_fmaak_f32 v15, v15, v11, 0xc0135761
	v_mul_f32_e32 v12, v12, v8
	v_mul_f32_e32 v13, v13, v9
	v_mul_f32_e32 v14, v14, v10
	v_mul_f32_e32 v15, v15, v11
	v_exp_f32_e32 v12, v12
	v_exp_f32_e32 v13, v13
	v_exp_f32_e32 v14, v14
	v_exp_f32_e32 v15, v15
	v_add_f32_e32 v12, 1.0, v12
	v_add_f32_e32 v13, 1.0, v13
	v_add_f32_e32 v14, 1.0, v14
	v_add_f32_e32 v15, 1.0, v15
	v_rcp_f32_e32 v12, v12
	v_rcp_f32_e32 v13, v13
	v_rcp_f32_e32 v14, v14
	v_rcp_f32_e32 v15, v15
	v_mul_f32_e32 v12, v12, v8
	v_mul_f32_e32 v13, v13, v9
	v_mul_f32_e32 v14, v14, v10
	v_mul_f32_e32 v15, v15, v11
	v_add_f32_e32 v5, v5, v12
	v_add_f32_e32 v21, v21, v13
	v_add_f32_e32 v23, v23, v14
	v_add_f32_e32 v25, v25, v15
	v_fmac_f32_e32 v4, v12, v12
	v_fmac_f32_e32 v20, v13, v13
	v_fmac_f32_e32 v22, v14, v14
	v_fmac_f32_e32 v24, v15, v15
	v_lshlrev_b32_e32 v8, 16, v180
	v_and_b32_e32 v9, 0xffff0000, v180
	v_lshlrev_b32_e32 v10, 16, v181
	v_and_b32_e32 v11, 0xffff0000, v181
	v_mul_f32_e32 v12, 0xbdd2d3e7, v8
	v_mul_f32_e32 v13, 0xbdd2d3e7, v9
	v_mul_f32_e32 v14, 0xbdd2d3e7, v10
	v_mul_f32_e32 v15, 0xbdd2d3e7, v11
	v_fmaak_f32 v12, v12, v8, 0xc0135761
	v_fmaak_f32 v13, v13, v9, 0xc0135761
	v_fmaak_f32 v14, v14, v10, 0xc0135761
	v_fmaak_f32 v15, v15, v11, 0xc0135761
	v_mul_f32_e32 v12, v12, v8
	v_mul_f32_e32 v13, v13, v9
	v_mul_f32_e32 v14, v14, v10
	v_mul_f32_e32 v15, v15, v11
	v_exp_f32_e32 v12, v12
	v_exp_f32_e32 v13, v13
	v_exp_f32_e32 v14, v14
	v_exp_f32_e32 v15, v15
	v_add_f32_e32 v12, 1.0, v12
	v_add_f32_e32 v13, 1.0, v13
	v_add_f32_e32 v14, 1.0, v14
	v_add_f32_e32 v15, 1.0, v15
	v_rcp_f32_e32 v12, v12
	v_rcp_f32_e32 v13, v13
	v_rcp_f32_e32 v14, v14
	v_rcp_f32_e32 v15, v15
	v_mul_f32_e32 v12, v12, v8
	v_mul_f32_e32 v13, v13, v9
	v_mul_f32_e32 v14, v14, v10
	v_mul_f32_e32 v15, v15, v11
	v_add_f32_e32 v5, v5, v12
	v_add_f32_e32 v21, v21, v13
	v_add_f32_e32 v23, v23, v14
	v_add_f32_e32 v25, v25, v15
	v_fmac_f32_e32 v4, v12, v12
	v_fmac_f32_e32 v20, v13, v13
	v_fmac_f32_e32 v22, v14, v14
	v_fmac_f32_e32 v24, v15, v15
	s_waitcnt vmcnt(6)
	v_lshlrev_b32_e32 v8, 16, v182
	v_and_b32_e32 v9, 0xffff0000, v182
	v_lshlrev_b32_e32 v10, 16, v183
	v_and_b32_e32 v11, 0xffff0000, v183
	v_mul_f32_e32 v12, 0xbdd2d3e7, v8
	v_mul_f32_e32 v13, 0xbdd2d3e7, v9
	v_mul_f32_e32 v14, 0xbdd2d3e7, v10
	v_mul_f32_e32 v15, 0xbdd2d3e7, v11
	v_fmaak_f32 v12, v12, v8, 0xc0135761
	v_fmaak_f32 v13, v13, v9, 0xc0135761
	v_fmaak_f32 v14, v14, v10, 0xc0135761
	v_fmaak_f32 v15, v15, v11, 0xc0135761
	v_mul_f32_e32 v12, v12, v8
	v_mul_f32_e32 v13, v13, v9
	v_mul_f32_e32 v14, v14, v10
	v_mul_f32_e32 v15, v15, v11
	v_exp_f32_e32 v12, v12
	v_exp_f32_e32 v13, v13
	v_exp_f32_e32 v14, v14
	v_exp_f32_e32 v15, v15
	v_add_f32_e32 v12, 1.0, v12
	v_add_f32_e32 v13, 1.0, v13
	v_add_f32_e32 v14, 1.0, v14
	v_add_f32_e32 v15, 1.0, v15
	v_rcp_f32_e32 v12, v12
	v_rcp_f32_e32 v13, v13
	v_rcp_f32_e32 v14, v14
	v_rcp_f32_e32 v15, v15
	v_mul_f32_e32 v12, v12, v8
	v_mul_f32_e32 v13, v13, v9
	v_mul_f32_e32 v14, v14, v10
	v_mul_f32_e32 v15, v15, v11
	v_add_f32_e32 v5, v5, v12
	v_add_f32_e32 v21, v21, v13
	v_add_f32_e32 v23, v23, v14
	v_add_f32_e32 v25, v25, v15
	v_fmac_f32_e32 v4, v12, v12
	v_fmac_f32_e32 v20, v13, v13
	v_fmac_f32_e32 v22, v14, v14
	v_fmac_f32_e32 v24, v15, v15
	v_lshlrev_b32_e32 v8, 16, v184
	v_and_b32_e32 v9, 0xffff0000, v184
	v_lshlrev_b32_e32 v10, 16, v185
	v_and_b32_e32 v11, 0xffff0000, v185
	v_mul_f32_e32 v12, 0xbdd2d3e7, v8
	v_mul_f32_e32 v13, 0xbdd2d3e7, v9
	v_mul_f32_e32 v14, 0xbdd2d3e7, v10
	v_mul_f32_e32 v15, 0xbdd2d3e7, v11
	v_fmaak_f32 v12, v12, v8, 0xc0135761
	v_fmaak_f32 v13, v13, v9, 0xc0135761
	v_fmaak_f32 v14, v14, v10, 0xc0135761
	v_fmaak_f32 v15, v15, v11, 0xc0135761
	v_mul_f32_e32 v12, v12, v8
	v_mul_f32_e32 v13, v13, v9
	v_mul_f32_e32 v14, v14, v10
	v_mul_f32_e32 v15, v15, v11
	v_exp_f32_e32 v12, v12
	v_exp_f32_e32 v13, v13
	v_exp_f32_e32 v14, v14
	v_exp_f32_e32 v15, v15
	v_add_f32_e32 v12, 1.0, v12
	v_add_f32_e32 v13, 1.0, v13
	v_add_f32_e32 v14, 1.0, v14
	v_add_f32_e32 v15, 1.0, v15
	v_rcp_f32_e32 v12, v12
	v_rcp_f32_e32 v13, v13
	v_rcp_f32_e32 v14, v14
	v_rcp_f32_e32 v15, v15
	v_mul_f32_e32 v12, v12, v8
	v_mul_f32_e32 v13, v13, v9
	v_mul_f32_e32 v14, v14, v10
	v_mul_f32_e32 v15, v15, v11
	v_add_f32_e32 v5, v5, v12
	v_add_f32_e32 v21, v21, v13
	v_add_f32_e32 v23, v23, v14
	v_add_f32_e32 v25, v25, v15
	v_fmac_f32_e32 v4, v12, v12
	v_fmac_f32_e32 v20, v13, v13
	v_fmac_f32_e32 v22, v14, v14
	v_fmac_f32_e32 v24, v15, v15
	s_waitcnt vmcnt(5)
	v_lshlrev_b32_e32 v8, 16, v186
	v_and_b32_e32 v9, 0xffff0000, v186
	v_lshlrev_b32_e32 v10, 16, v187
	v_and_b32_e32 v11, 0xffff0000, v187
	v_mul_f32_e32 v12, 0xbdd2d3e7, v8
	v_mul_f32_e32 v13, 0xbdd2d3e7, v9
	v_mul_f32_e32 v14, 0xbdd2d3e7, v10
	v_mul_f32_e32 v15, 0xbdd2d3e7, v11
	v_fmaak_f32 v12, v12, v8, 0xc0135761
	v_fmaak_f32 v13, v13, v9, 0xc0135761
	v_fmaak_f32 v14, v14, v10, 0xc0135761
	v_fmaak_f32 v15, v15, v11, 0xc0135761
	v_mul_f32_e32 v12, v12, v8
	v_mul_f32_e32 v13, v13, v9
	v_mul_f32_e32 v14, v14, v10
	v_mul_f32_e32 v15, v15, v11
	v_exp_f32_e32 v12, v12
	v_exp_f32_e32 v13, v13
	v_exp_f32_e32 v14, v14
	v_exp_f32_e32 v15, v15
	v_add_f32_e32 v12, 1.0, v12
	v_add_f32_e32 v13, 1.0, v13
	v_add_f32_e32 v14, 1.0, v14
	v_add_f32_e32 v15, 1.0, v15
	v_rcp_f32_e32 v12, v12
	v_rcp_f32_e32 v13, v13
	v_rcp_f32_e32 v14, v14
	v_rcp_f32_e32 v15, v15
	v_mul_f32_e32 v12, v12, v8
	v_mul_f32_e32 v13, v13, v9
	v_mul_f32_e32 v14, v14, v10
	v_mul_f32_e32 v15, v15, v11
	v_add_f32_e32 v5, v5, v12
	v_add_f32_e32 v21, v21, v13
	v_add_f32_e32 v23, v23, v14
	v_add_f32_e32 v25, v25, v15
	v_fmac_f32_e32 v4, v12, v12
	v_fmac_f32_e32 v20, v13, v13
	v_fmac_f32_e32 v22, v14, v14
	v_fmac_f32_e32 v24, v15, v15
	v_lshlrev_b32_e32 v8, 16, v188
	v_and_b32_e32 v9, 0xffff0000, v188
	v_lshlrev_b32_e32 v10, 16, v189
	v_and_b32_e32 v11, 0xffff0000, v189
	v_mul_f32_e32 v12, 0xbdd2d3e7, v8
	v_mul_f32_e32 v13, 0xbdd2d3e7, v9
	v_mul_f32_e32 v14, 0xbdd2d3e7, v10
	v_mul_f32_e32 v15, 0xbdd2d3e7, v11
	v_fmaak_f32 v12, v12, v8, 0xc0135761
	v_fmaak_f32 v13, v13, v9, 0xc0135761
	v_fmaak_f32 v14, v14, v10, 0xc0135761
	v_fmaak_f32 v15, v15, v11, 0xc0135761
	v_mul_f32_e32 v12, v12, v8
	v_mul_f32_e32 v13, v13, v9
	v_mul_f32_e32 v14, v14, v10
	v_mul_f32_e32 v15, v15, v11
	v_exp_f32_e32 v12, v12
	v_exp_f32_e32 v13, v13
	v_exp_f32_e32 v14, v14
	v_exp_f32_e32 v15, v15
	v_add_f32_e32 v12, 1.0, v12
	v_add_f32_e32 v13, 1.0, v13
	v_add_f32_e32 v14, 1.0, v14
	v_add_f32_e32 v15, 1.0, v15
	v_rcp_f32_e32 v12, v12
	v_rcp_f32_e32 v13, v13
	v_rcp_f32_e32 v14, v14
	v_rcp_f32_e32 v15, v15
	v_mul_f32_e32 v12, v12, v8
	v_mul_f32_e32 v13, v13, v9
	v_mul_f32_e32 v14, v14, v10
	v_mul_f32_e32 v15, v15, v11
	v_add_f32_e32 v5, v5, v12
	v_add_f32_e32 v21, v21, v13
	v_add_f32_e32 v23, v23, v14
	v_add_f32_e32 v25, v25, v15
	v_fmac_f32_e32 v4, v12, v12
	v_fmac_f32_e32 v20, v13, v13
	v_fmac_f32_e32 v22, v14, v14
	v_fmac_f32_e32 v24, v15, v15
	s_waitcnt vmcnt(4)
	v_lshlrev_b32_e32 v8, 16, v190
	v_and_b32_e32 v9, 0xffff0000, v190
	v_lshlrev_b32_e32 v10, 16, v191
	v_and_b32_e32 v11, 0xffff0000, v191
	v_mul_f32_e32 v12, 0xbdd2d3e7, v8
	v_mul_f32_e32 v13, 0xbdd2d3e7, v9
	v_mul_f32_e32 v14, 0xbdd2d3e7, v10
	v_mul_f32_e32 v15, 0xbdd2d3e7, v11
	v_fmaak_f32 v12, v12, v8, 0xc0135761
	v_fmaak_f32 v13, v13, v9, 0xc0135761
	v_fmaak_f32 v14, v14, v10, 0xc0135761
	v_fmaak_f32 v15, v15, v11, 0xc0135761
	v_mul_f32_e32 v12, v12, v8
	v_mul_f32_e32 v13, v13, v9
	v_mul_f32_e32 v14, v14, v10
	v_mul_f32_e32 v15, v15, v11
	v_exp_f32_e32 v12, v12
	v_exp_f32_e32 v13, v13
	v_exp_f32_e32 v14, v14
	v_exp_f32_e32 v15, v15
	v_add_f32_e32 v12, 1.0, v12
	v_add_f32_e32 v13, 1.0, v13
	v_add_f32_e32 v14, 1.0, v14
	v_add_f32_e32 v15, 1.0, v15
	v_rcp_f32_e32 v12, v12
	v_rcp_f32_e32 v13, v13
	v_rcp_f32_e32 v14, v14
	v_rcp_f32_e32 v15, v15
	v_mul_f32_e32 v12, v12, v8
	v_mul_f32_e32 v13, v13, v9
	v_mul_f32_e32 v14, v14, v10
	v_mul_f32_e32 v15, v15, v11
	v_add_f32_e32 v5, v5, v12
	v_add_f32_e32 v21, v21, v13
	v_add_f32_e32 v23, v23, v14
	v_add_f32_e32 v25, v25, v15
	v_fmac_f32_e32 v4, v12, v12
	v_fmac_f32_e32 v20, v13, v13
	v_fmac_f32_e32 v22, v14, v14
	v_fmac_f32_e32 v24, v15, v15
	v_lshlrev_b32_e32 v8, 16, v192
	v_and_b32_e32 v9, 0xffff0000, v192
	v_lshlrev_b32_e32 v10, 16, v193
	v_and_b32_e32 v11, 0xffff0000, v193
	v_mul_f32_e32 v12, 0xbdd2d3e7, v8
	v_mul_f32_e32 v13, 0xbdd2d3e7, v9
	v_mul_f32_e32 v14, 0xbdd2d3e7, v10
	v_mul_f32_e32 v15, 0xbdd2d3e7, v11
	v_fmaak_f32 v12, v12, v8, 0xc0135761
	v_fmaak_f32 v13, v13, v9, 0xc0135761
	v_fmaak_f32 v14, v14, v10, 0xc0135761
	v_fmaak_f32 v15, v15, v11, 0xc0135761
	v_mul_f32_e32 v12, v12, v8
	v_mul_f32_e32 v13, v13, v9
	v_mul_f32_e32 v14, v14, v10
	v_mul_f32_e32 v15, v15, v11
	v_exp_f32_e32 v12, v12
	v_exp_f32_e32 v13, v13
	v_exp_f32_e32 v14, v14
	v_exp_f32_e32 v15, v15
	v_add_f32_e32 v12, 1.0, v12
	v_add_f32_e32 v13, 1.0, v13
	v_add_f32_e32 v14, 1.0, v14
	v_add_f32_e32 v15, 1.0, v15
	v_rcp_f32_e32 v12, v12
	v_rcp_f32_e32 v13, v13
	v_rcp_f32_e32 v14, v14
	v_rcp_f32_e32 v15, v15
	v_mul_f32_e32 v12, v12, v8
	v_mul_f32_e32 v13, v13, v9
	v_mul_f32_e32 v14, v14, v10
	v_mul_f32_e32 v15, v15, v11
	v_add_f32_e32 v5, v5, v12
	v_add_f32_e32 v21, v21, v13
	v_add_f32_e32 v23, v23, v14
	v_add_f32_e32 v25, v25, v15
	v_fmac_f32_e32 v4, v12, v12
	v_fmac_f32_e32 v20, v13, v13
	v_fmac_f32_e32 v22, v14, v14
	v_fmac_f32_e32 v24, v15, v15
	s_waitcnt vmcnt(3)
	v_lshlrev_b32_e32 v8, 16, v194
	v_and_b32_e32 v9, 0xffff0000, v194
	v_lshlrev_b32_e32 v10, 16, v195
	v_and_b32_e32 v11, 0xffff0000, v195
	v_mul_f32_e32 v12, 0xbdd2d3e7, v8
	v_mul_f32_e32 v13, 0xbdd2d3e7, v9
	v_mul_f32_e32 v14, 0xbdd2d3e7, v10
	v_mul_f32_e32 v15, 0xbdd2d3e7, v11
	v_fmaak_f32 v12, v12, v8, 0xc0135761
	v_fmaak_f32 v13, v13, v9, 0xc0135761
	v_fmaak_f32 v14, v14, v10, 0xc0135761
	v_fmaak_f32 v15, v15, v11, 0xc0135761
	v_mul_f32_e32 v12, v12, v8
	v_mul_f32_e32 v13, v13, v9
	v_mul_f32_e32 v14, v14, v10
	v_mul_f32_e32 v15, v15, v11
	v_exp_f32_e32 v12, v12
	v_exp_f32_e32 v13, v13
	v_exp_f32_e32 v14, v14
	v_exp_f32_e32 v15, v15
	v_add_f32_e32 v12, 1.0, v12
	v_add_f32_e32 v13, 1.0, v13
	v_add_f32_e32 v14, 1.0, v14
	v_add_f32_e32 v15, 1.0, v15
	v_rcp_f32_e32 v12, v12
	v_rcp_f32_e32 v13, v13
	v_rcp_f32_e32 v14, v14
	v_rcp_f32_e32 v15, v15
	v_mul_f32_e32 v12, v12, v8
	v_mul_f32_e32 v13, v13, v9
	v_mul_f32_e32 v14, v14, v10
	v_mul_f32_e32 v15, v15, v11
	v_add_f32_e32 v5, v5, v12
	v_add_f32_e32 v21, v21, v13
	v_add_f32_e32 v23, v23, v14
	v_add_f32_e32 v25, v25, v15
	v_fmac_f32_e32 v4, v12, v12
	v_fmac_f32_e32 v20, v13, v13
	v_fmac_f32_e32 v22, v14, v14
	v_fmac_f32_e32 v24, v15, v15
	v_lshlrev_b32_e32 v8, 16, v196
	v_and_b32_e32 v9, 0xffff0000, v196
	v_lshlrev_b32_e32 v10, 16, v197
	v_and_b32_e32 v11, 0xffff0000, v197
	v_mul_f32_e32 v12, 0xbdd2d3e7, v8
	v_mul_f32_e32 v13, 0xbdd2d3e7, v9
	v_mul_f32_e32 v14, 0xbdd2d3e7, v10
	v_mul_f32_e32 v15, 0xbdd2d3e7, v11
	v_fmaak_f32 v12, v12, v8, 0xc0135761
	v_fmaak_f32 v13, v13, v9, 0xc0135761
	v_fmaak_f32 v14, v14, v10, 0xc0135761
	v_fmaak_f32 v15, v15, v11, 0xc0135761
	v_mul_f32_e32 v12, v12, v8
	v_mul_f32_e32 v13, v13, v9
	v_mul_f32_e32 v14, v14, v10
	v_mul_f32_e32 v15, v15, v11
	v_exp_f32_e32 v12, v12
	v_exp_f32_e32 v13, v13
	v_exp_f32_e32 v14, v14
	v_exp_f32_e32 v15, v15
	v_add_f32_e32 v12, 1.0, v12
	v_add_f32_e32 v13, 1.0, v13
	v_add_f32_e32 v14, 1.0, v14
	v_add_f32_e32 v15, 1.0, v15
	v_rcp_f32_e32 v12, v12
	v_rcp_f32_e32 v13, v13
	v_rcp_f32_e32 v14, v14
	v_rcp_f32_e32 v15, v15
	v_mul_f32_e32 v12, v12, v8
	v_mul_f32_e32 v13, v13, v9
	v_mul_f32_e32 v14, v14, v10
	v_mul_f32_e32 v15, v15, v11
	v_add_f32_e32 v5, v5, v12
	v_add_f32_e32 v21, v21, v13
	v_add_f32_e32 v23, v23, v14
	v_add_f32_e32 v25, v25, v15
	v_fmac_f32_e32 v4, v12, v12
	v_fmac_f32_e32 v20, v13, v13
	v_fmac_f32_e32 v22, v14, v14
	v_fmac_f32_e32 v24, v15, v15
	s_waitcnt vmcnt(2)
	v_lshlrev_b32_e32 v8, 16, v198
	v_and_b32_e32 v9, 0xffff0000, v198
	v_lshlrev_b32_e32 v10, 16, v199
	v_and_b32_e32 v11, 0xffff0000, v199
	v_mul_f32_e32 v12, 0xbdd2d3e7, v8
	v_mul_f32_e32 v13, 0xbdd2d3e7, v9
	v_mul_f32_e32 v14, 0xbdd2d3e7, v10
	v_mul_f32_e32 v15, 0xbdd2d3e7, v11
	v_fmaak_f32 v12, v12, v8, 0xc0135761
	v_fmaak_f32 v13, v13, v9, 0xc0135761
	v_fmaak_f32 v14, v14, v10, 0xc0135761
	v_fmaak_f32 v15, v15, v11, 0xc0135761
	v_mul_f32_e32 v12, v12, v8
	v_mul_f32_e32 v13, v13, v9
	v_mul_f32_e32 v14, v14, v10
	v_mul_f32_e32 v15, v15, v11
	v_exp_f32_e32 v12, v12
	v_exp_f32_e32 v13, v13
	v_exp_f32_e32 v14, v14
	v_exp_f32_e32 v15, v15
	v_add_f32_e32 v12, 1.0, v12
	v_add_f32_e32 v13, 1.0, v13
	v_add_f32_e32 v14, 1.0, v14
	v_add_f32_e32 v15, 1.0, v15
	v_rcp_f32_e32 v12, v12
	v_rcp_f32_e32 v13, v13
	v_rcp_f32_e32 v14, v14
	v_rcp_f32_e32 v15, v15
	v_mul_f32_e32 v12, v12, v8
	v_mul_f32_e32 v13, v13, v9
	v_mul_f32_e32 v14, v14, v10
	v_mul_f32_e32 v15, v15, v11
	v_add_f32_e32 v5, v5, v12
	v_add_f32_e32 v21, v21, v13
	v_add_f32_e32 v23, v23, v14
	v_add_f32_e32 v25, v25, v15
	v_fmac_f32_e32 v4, v12, v12
	v_fmac_f32_e32 v20, v13, v13
	v_fmac_f32_e32 v22, v14, v14
	v_fmac_f32_e32 v24, v15, v15
	v_lshlrev_b32_e32 v8, 16, v200
	v_and_b32_e32 v9, 0xffff0000, v200
	v_lshlrev_b32_e32 v10, 16, v201
	v_and_b32_e32 v11, 0xffff0000, v201
	v_mul_f32_e32 v12, 0xbdd2d3e7, v8
	v_mul_f32_e32 v13, 0xbdd2d3e7, v9
	v_mul_f32_e32 v14, 0xbdd2d3e7, v10
	v_mul_f32_e32 v15, 0xbdd2d3e7, v11
	v_fmaak_f32 v12, v12, v8, 0xc0135761
	v_fmaak_f32 v13, v13, v9, 0xc0135761
	v_fmaak_f32 v14, v14, v10, 0xc0135761
	v_fmaak_f32 v15, v15, v11, 0xc0135761
	v_mul_f32_e32 v12, v12, v8
	v_mul_f32_e32 v13, v13, v9
	v_mul_f32_e32 v14, v14, v10
	v_mul_f32_e32 v15, v15, v11
	v_exp_f32_e32 v12, v12
	v_exp_f32_e32 v13, v13
	v_exp_f32_e32 v14, v14
	v_exp_f32_e32 v15, v15
	v_add_f32_e32 v12, 1.0, v12
	v_add_f32_e32 v13, 1.0, v13
	v_add_f32_e32 v14, 1.0, v14
	v_add_f32_e32 v15, 1.0, v15
	v_rcp_f32_e32 v12, v12
	v_rcp_f32_e32 v13, v13
	v_rcp_f32_e32 v14, v14
	v_rcp_f32_e32 v15, v15
	v_mul_f32_e32 v12, v12, v8
	v_mul_f32_e32 v13, v13, v9
	v_mul_f32_e32 v14, v14, v10
	v_mul_f32_e32 v15, v15, v11
	v_add_f32_e32 v5, v5, v12
	v_add_f32_e32 v21, v21, v13
	v_add_f32_e32 v23, v23, v14
	v_add_f32_e32 v25, v25, v15
	v_fmac_f32_e32 v4, v12, v12
	v_fmac_f32_e32 v20, v13, v13
	v_fmac_f32_e32 v22, v14, v14
	v_fmac_f32_e32 v24, v15, v15
	s_waitcnt vmcnt(1)
	v_lshlrev_b32_e32 v8, 16, v202
	v_and_b32_e32 v9, 0xffff0000, v202
	v_lshlrev_b32_e32 v10, 16, v203
	v_and_b32_e32 v11, 0xffff0000, v203
	v_mul_f32_e32 v12, 0xbdd2d3e7, v8
	v_mul_f32_e32 v13, 0xbdd2d3e7, v9
	v_mul_f32_e32 v14, 0xbdd2d3e7, v10
	v_mul_f32_e32 v15, 0xbdd2d3e7, v11
	v_fmaak_f32 v12, v12, v8, 0xc0135761
	v_fmaak_f32 v13, v13, v9, 0xc0135761
	v_fmaak_f32 v14, v14, v10, 0xc0135761
	v_fmaak_f32 v15, v15, v11, 0xc0135761
	v_mul_f32_e32 v12, v12, v8
	v_mul_f32_e32 v13, v13, v9
	v_mul_f32_e32 v14, v14, v10
	v_mul_f32_e32 v15, v15, v11
	v_exp_f32_e32 v12, v12
	v_exp_f32_e32 v13, v13
	v_exp_f32_e32 v14, v14
	v_exp_f32_e32 v15, v15
	v_add_f32_e32 v12, 1.0, v12
	v_add_f32_e32 v13, 1.0, v13
	v_add_f32_e32 v14, 1.0, v14
	v_add_f32_e32 v15, 1.0, v15
	v_rcp_f32_e32 v12, v12
	v_rcp_f32_e32 v13, v13
	v_rcp_f32_e32 v14, v14
	v_rcp_f32_e32 v15, v15
	v_mul_f32_e32 v12, v12, v8
	v_mul_f32_e32 v13, v13, v9
	v_mul_f32_e32 v14, v14, v10
	v_mul_f32_e32 v15, v15, v11
	v_add_f32_e32 v5, v5, v12
	v_add_f32_e32 v21, v21, v13
	v_add_f32_e32 v23, v23, v14
	v_add_f32_e32 v25, v25, v15
	v_fmac_f32_e32 v4, v12, v12
	v_fmac_f32_e32 v20, v13, v13
	v_fmac_f32_e32 v22, v14, v14
	v_fmac_f32_e32 v24, v15, v15
	v_lshlrev_b32_e32 v8, 16, v204
	v_and_b32_e32 v9, 0xffff0000, v204
	v_lshlrev_b32_e32 v10, 16, v205
	v_and_b32_e32 v11, 0xffff0000, v205
	v_mul_f32_e32 v12, 0xbdd2d3e7, v8
	v_mul_f32_e32 v13, 0xbdd2d3e7, v9
	v_mul_f32_e32 v14, 0xbdd2d3e7, v10
	v_mul_f32_e32 v15, 0xbdd2d3e7, v11
	v_fmaak_f32 v12, v12, v8, 0xc0135761
	v_fmaak_f32 v13, v13, v9, 0xc0135761
	v_fmaak_f32 v14, v14, v10, 0xc0135761
	v_fmaak_f32 v15, v15, v11, 0xc0135761
	v_mul_f32_e32 v12, v12, v8
	v_mul_f32_e32 v13, v13, v9
	v_mul_f32_e32 v14, v14, v10
	v_mul_f32_e32 v15, v15, v11
	v_exp_f32_e32 v12, v12
	v_exp_f32_e32 v13, v13
	v_exp_f32_e32 v14, v14
	v_exp_f32_e32 v15, v15
	v_add_f32_e32 v12, 1.0, v12
	v_add_f32_e32 v13, 1.0, v13
	v_add_f32_e32 v14, 1.0, v14
	v_add_f32_e32 v15, 1.0, v15
	v_rcp_f32_e32 v12, v12
	v_rcp_f32_e32 v13, v13
	v_rcp_f32_e32 v14, v14
	v_rcp_f32_e32 v15, v15
	v_mul_f32_e32 v12, v12, v8
	v_mul_f32_e32 v13, v13, v9
	v_mul_f32_e32 v14, v14, v10
	v_mul_f32_e32 v15, v15, v11
	v_add_f32_e32 v5, v5, v12
	v_add_f32_e32 v21, v21, v13
	v_add_f32_e32 v23, v23, v14
	v_add_f32_e32 v25, v25, v15
	v_fmac_f32_e32 v4, v12, v12
	v_fmac_f32_e32 v20, v13, v13
	v_fmac_f32_e32 v22, v14, v14
	v_fmac_f32_e32 v24, v15, v15
	s_waitcnt vmcnt(0)
	v_lshlrev_b32_e32 v8, 16, v206
	v_and_b32_e32 v9, 0xffff0000, v206
	v_lshlrev_b32_e32 v10, 16, v207
	v_and_b32_e32 v11, 0xffff0000, v207
	v_mul_f32_e32 v12, 0xbdd2d3e7, v8
	v_mul_f32_e32 v13, 0xbdd2d3e7, v9
	v_mul_f32_e32 v14, 0xbdd2d3e7, v10
	v_mul_f32_e32 v15, 0xbdd2d3e7, v11
	v_fmaak_f32 v12, v12, v8, 0xc0135761
	v_fmaak_f32 v13, v13, v9, 0xc0135761
	v_fmaak_f32 v14, v14, v10, 0xc0135761
	v_fmaak_f32 v15, v15, v11, 0xc0135761
	v_mul_f32_e32 v12, v12, v8
	v_mul_f32_e32 v13, v13, v9
	v_mul_f32_e32 v14, v14, v10
	v_mul_f32_e32 v15, v15, v11
	v_exp_f32_e32 v12, v12
	v_exp_f32_e32 v13, v13
	v_exp_f32_e32 v14, v14
	v_exp_f32_e32 v15, v15
	v_add_f32_e32 v12, 1.0, v12
	v_add_f32_e32 v13, 1.0, v13
	v_add_f32_e32 v14, 1.0, v14
	v_add_f32_e32 v15, 1.0, v15
	v_rcp_f32_e32 v12, v12
	v_rcp_f32_e32 v13, v13
	v_rcp_f32_e32 v14, v14
	v_rcp_f32_e32 v15, v15
	v_mul_f32_e32 v12, v12, v8
	v_mul_f32_e32 v13, v13, v9
	v_mul_f32_e32 v14, v14, v10
	v_mul_f32_e32 v15, v15, v11
	v_add_f32_e32 v5, v5, v12
	v_add_f32_e32 v21, v21, v13
	v_add_f32_e32 v23, v23, v14
	v_add_f32_e32 v25, v25, v15
	v_fmac_f32_e32 v4, v12, v12
	v_fmac_f32_e32 v20, v13, v13
	v_fmac_f32_e32 v22, v14, v14
	v_fmac_f32_e32 v24, v15, v15
	v_lshlrev_b32_e32 v8, 16, v208
	v_and_b32_e32 v9, 0xffff0000, v208
	v_lshlrev_b32_e32 v10, 16, v209
	v_and_b32_e32 v11, 0xffff0000, v209
	v_mul_f32_e32 v12, 0xbdd2d3e7, v8
	v_mul_f32_e32 v13, 0xbdd2d3e7, v9
	v_mul_f32_e32 v14, 0xbdd2d3e7, v10
	v_mul_f32_e32 v15, 0xbdd2d3e7, v11
	v_fmaak_f32 v12, v12, v8, 0xc0135761
	v_fmaak_f32 v13, v13, v9, 0xc0135761
	v_fmaak_f32 v14, v14, v10, 0xc0135761
	v_fmaak_f32 v15, v15, v11, 0xc0135761
	v_mul_f32_e32 v12, v12, v8
	v_mul_f32_e32 v13, v13, v9
	v_mul_f32_e32 v14, v14, v10
	v_mul_f32_e32 v15, v15, v11
	v_exp_f32_e32 v12, v12
	v_exp_f32_e32 v13, v13
	v_exp_f32_e32 v14, v14
	v_exp_f32_e32 v15, v15
	v_add_f32_e32 v12, 1.0, v12
	v_add_f32_e32 v13, 1.0, v13
	v_add_f32_e32 v14, 1.0, v14
	v_add_f32_e32 v15, 1.0, v15
	v_rcp_f32_e32 v12, v12
	v_rcp_f32_e32 v13, v13
	v_rcp_f32_e32 v14, v14
	v_rcp_f32_e32 v15, v15
	v_mul_f32_e32 v12, v12, v8
	v_mul_f32_e32 v13, v13, v9
	v_mul_f32_e32 v14, v14, v10
	v_mul_f32_e32 v15, v15, v11
	v_add_f32_e32 v5, v5, v12
	v_add_f32_e32 v21, v21, v13
	v_add_f32_e32 v23, v23, v14
	v_add_f32_e32 v25, v25, v15
	v_fmac_f32_e32 v4, v12, v12
	v_fmac_f32_e32 v20, v13, v13
	v_fmac_f32_e32 v22, v14, v14
	v_fmac_f32_e32 v24, v15, v15
	v_pk_add_f32 v[4:5], v[4:5], v[20:21]
	v_pk_add_f32 v[22:23], v[22:23], v[24:25]
	s_nop 0
	v_pk_add_f32 v[4:5], v[4:5], v[22:23]
	ds_bpermute_b32 v3, v159, v5
	ds_bpermute_b32 v2, v159, v4
	s_waitcnt lgkmcnt(0)
	v_pk_add_f32 v[2:3], v[4:5], v[2:3]
	ds_bpermute_b32 v5, v162, v3
	ds_bpermute_b32 v4, v162, v2
	s_and_saveexec_b64 s[48:49], s[62:63]
	s_cbranch_execz .LBB0_122
	s_waitcnt lgkmcnt(0)
	v_pk_add_f32 v[2:3], v[2:3], v[4:5]
	s_mov_b32 s58, 0x3b000000
	v_pk_mul_f32 v[2:3], v[2:3], s[58:59] op_sel_hi:[1,0]
	s_nop 0
	v_fma_f32 v2, -v3, v3, v2
	v_max_f32_e32 v2, 0, v2
	v_add_f32_e32 v2, 0x3727c5ac, v2
	v_mul_f32_e32 v4, 0x4b800000, v2
	v_cmp_gt_f32_e32 vcc, s33, v2
	s_nop 1
	v_cndmask_b32_e32 v2, v2, v4, vcc
	v_rsq_f32_e32 v2, v2
	s_nop 0
	v_mul_f32_e32 v4, 0x45800000, v2
	v_cndmask_b32_e32 v5, v2, v4, vcc
	v_mov_b32_e32 v4, v3
	ds_write_b64 v175, v[4:5]

.LBB0_159:
	s_and_b64 vcc, exec, s[4:5]
	s_cbranch_vccz .Lscan_nostage
	s_xor_b32 s6, s11, 1
	s_mul_i32 s6, s6, 0x12000
	v_lshl_add_u64 v[2:3], s[2:3], 0, v[52:53]
	s_mov_b64 s[12:13], 0x17c04000
	s_add_i32 s6, s6, s8
	v_lshl_add_u64 v[62:63], v[2:3], 0, s[12:13]
	s_add_i32 s6, s6, 0
	s_mov_b32 s7, m0
	s_mov_b32 m0, s6
	s_nop 0
	global_load_lds_dwordx4 v[62:63], off
	s_mov_b32 m0, s7
	v_lshl_add_u64 v[62:63], s[2:3], 0, v[50:51]
	v_lshl_add_u64 v[64:65], v[62:63], 0, s[12:13]
	s_add_i32 s7, s6, 0x2000
	s_mov_b32 s12, m0
	s_mov_b32 m0, s7
	s_nop 0
	global_load_lds_dwordx4 v[64:65], off
	s_mov_b32 m0, s12
	s_mov_b64 s[14:15], 0x15c04000
	v_lshl_add_u64 v[2:3], v[2:3], 0, s[14:15]
	s_add_i32 s7, s6, 0x4000
	s_mov_b32 s12, m0
	s_mov_b32 m0, s7
	s_nop 0
	global_load_lds_dwordx4 v[2:3], off
	s_mov_b32 m0, s12
	v_lshl_add_u64 v[2:3], v[62:63], 0, s[14:15]
	s_add_i32 s7, s6, 0x6000
	s_mov_b32 s12, m0
	s_mov_b32 m0, s7
	s_nop 0
	global_load_lds_dwordx4 v[2:3], off
	s_mov_b32 m0, s12
	v_lshl_add_u64 v[2:3], s[2:3], 0, v[48:49]
	s_add_i32 s7, s6, 0x8000
	s_mov_b32 s12, m0
	s_mov_b32 m0, s7
	s_nop 0
	global_load_lds_dwordx4 v[2:3], off
	s_mov_b32 m0, s12
	v_lshl_add_u64 v[2:3], s[2:3], 0, v[46:47]
	s_add_i32 s7, s6, 0xa000
	s_mov_b32 s12, m0
	s_mov_b32 m0, s7
	s_nop 0
	global_load_lds_dwordx4 v[2:3], off
	s_mov_b32 m0, s12
	v_lshl_add_u64 v[2:3], s[2:3], 0, v[44:45]
	s_add_i32 s7, s6, 0xc000
	s_mov_b32 s12, m0
	s_mov_b32 m0, s7
	s_nop 0
	global_load_lds_dwordx4 v[2:3], off
	s_mov_b32 m0, s12
	v_lshl_add_u64 v[2:3], s[2:3], 0, v[42:43]
	s_add_i32 s7, s6, 0xe000
	s_mov_b32 s12, m0
	s_mov_b32 m0, s7
	s_nop 0
	global_load_lds_dwordx4 v[2:3], off
	s_mov_b32 m0, s12
	v_lshl_add_u64 v[2:3], s[2:3], 0, v[40:41]
	s_add_i32 s6, s6, 0x10000
	s_mov_b32 s7, m0
	s_mov_b32 m0, s6
	s_nop 0
	global_load_lds_dwordx4 v[2:3], off
	s_mov_b32 m0, s7
	s_mov_b32 s7, m0
	s_xor_b32 s6, s11, 1
	s_mul_i32 s6, s6, 0x12000
	s_add_i32 s6, s6, s8
	s_addk_i32 s6, 0xf000
	s_add_u32 s12, s2, 0xfffff000
	s_addc_u32 s13, s3, -1
	s_mov_b64 s[14:15], 0x17c04000
	v_lshl_add_u64 v[2:3], s[12:13], 0, v[52:53]
	v_lshl_add_u64 v[64:65], s[12:13], 0, v[50:51]
	v_lshl_add_u64 v[62:63], v[2:3], 0, s[14:15]
	s_mov_b32 m0, s6
	s_nop 0
	global_load_lds_dwordx4 v[62:63], off
	v_lshl_add_u64 v[62:63], v[64:65], 0, s[14:15]
	s_add_i32 m0, s6, 0x2000
	s_mov_b64 s[14:15], 0x15c04000
	global_load_lds_dwordx4 v[62:63], off
	v_lshl_add_u64 v[62:63], v[2:3], 0, s[14:15]
	s_add_i32 m0, s6, 0x4000
	s_nop 0
	global_load_lds_dwordx4 v[62:63], off
	v_lshl_add_u64 v[62:63], v[64:65], 0, s[14:15]
	s_add_i32 m0, s6, 0x6000
	s_nop 0
	global_load_lds_dwordx4 v[62:63], off
	v_lshl_add_u64 v[2:3], s[12:13], 0, v[48:49]
	s_add_i32 m0, s6, 0x8000
	s_nop 0
	global_load_lds_dwordx4 v[2:3], off
	v_lshl_add_u64 v[2:3], s[12:13], 0, v[46:47]
	s_add_i32 m0, s6, 0xa000
	s_nop 0
	global_load_lds_dwordx4 v[2:3], off
	v_lshl_add_u64 v[2:3], s[12:13], 0, v[44:45]
	s_add_i32 m0, s6, 0xc000
	s_nop 0
	global_load_lds_dwordx4 v[2:3], off
	s_add_u32 s12, s12, 0xfffff000
	s_addc_u32 s13, s13, -1
	v_lshl_add_u64 v[2:3], s[12:13], 0, v[42:43]
	s_add_i32 m0, s6, 0xe000
	s_nop 0
	global_load_lds_dwordx4 v[2:3], off
	v_lshl_add_u64 v[2:3], s[12:13], 0, v[40:41]
	s_add_i32 m0, s6, 0x10000
	s_nop 0
	global_load_lds_dwordx4 v[2:3], off
	s_mov_b32 m0, s7
.Lscan_nostage:
	s_mov_b64 s[6:7], -1
	s_and_b64 vcc, exec, s[4:5]
	s_cbranch_vccz .LBB0_161
	s_waitcnt vmcnt(0) lgkmcnt(0)
	s_barrier
	s_mov_b64 s[6:7], 0
